# stack: SwiGLU packed epilogue + barrier leader XGEN-before-inv + attention K/V staging loads issued together
# baseline (speedup 1.0000x reference)
; __device__ __forceinline__ unsigned xb_ld(unsigned* p)              { return __hip_atomic_load(p, __ATOMIC_RELAXED, __HIP_MEMORY_SCOPE_AGENT); }
; __device__ __forceinline__ unsigned xb_add(unsigned* p, unsigned v) { return __hip_atomic_fetch_add(p, v, __ATOMIC_RELAXED, __HIP_MEMORY_SCOPE_AGENT); }
; #define XB_SPIN(cond, bar) do { unsigned _sp = 0; while (cond) { __builtin_amdgcn_s_sleep(1); \
;     if ((++_sp & 255u) == 0u) { if (xb_ld(&(bar)[XB_TMO])) break; if (_sp > XB_SPIN_CAP) { atomicAdd(&(bar)[XB_TMO], 1u); break; } } } } while (0)
; __device__ __forceinline__ void xcd_barrier(const XcdBarrier& b) {
;     ...
;             __builtin_amdgcn_fence(__ATOMIC_RELEASE, "agent");
;             asm volatile("s_waitcnt vmcnt(0)" ::: "memory");
;             const unsigned og = xb_add(&bar[XB_TOP], 1u);
;             const unsigned tg = og / nx;
;             if (og + 1u == (tg + 1u) * nx) xb_add(&bar[XB_TOPGEN], 1u);
;             else XB_SPIN(xb_ld(&bar[XB_TOPGEN]) == tg, bar);
;             __builtin_amdgcn_fence(__ATOMIC_ACQUIRE, "agent");
;             xb_add(&bar[XB_XGEN(bx)], 1u);
;             asm volatile("s_waitcnt vmcnt(0)" ::: "memory");
.LBB0_639:
	s_or_b64 exec, exec, s[2:3]
	s_mov_b64 s[2:3], exec
	v_mbcnt_lo_u32_b32 v2, s2, 0
	v_mbcnt_hi_u32_b32 v2, s3, v2
	s_mov_b32 s7, 0
	v_cmp_eq_u32_e32 vcc, 0, v2
	s_waitcnt vmcnt(0)
	s_and_saveexec_b64 s[4:5], vcc
	s_cbranch_execz .LBB0_641
	s_add_i32 s6, s21, 0x900
	s_lshl_b64 s[6:7], s[6:7], 2
	s_add_u32 s6, s78, s6
	s_addc_u32 s7, s79, s7
	s_bcnt1_i32_b64 s2, s[2:3]
	v_mov_b32_e32 v2, 0
	v_mov_b32_e32 v3, s2
	global_atomic_add v2, v3, s[6:7]
.LBB0_641:
	s_or_b64 exec, exec, s[4:5]
	buffer_inv sc1
	s_waitcnt vmcnt(0)

; __device__ __forceinline__ unsigned xb_ld(unsigned* p)              { return __hip_atomic_load(p, __ATOMIC_RELAXED, __HIP_MEMORY_SCOPE_AGENT); }
; __device__ __forceinline__ unsigned xb_add(unsigned* p, unsigned v) { return __hip_atomic_fetch_add(p, v, __ATOMIC_RELAXED, __HIP_MEMORY_SCOPE_AGENT); }
; #define XB_SPIN(cond, bar) do { unsigned _sp = 0; while (cond) { __builtin_amdgcn_s_sleep(1); \
;     if ((++_sp & 255u) == 0u) { if (xb_ld(&(bar)[XB_TMO])) break; if (_sp > XB_SPIN_CAP) { atomicAdd(&(bar)[XB_TMO], 1u); break; } } } } while (0)
; __device__ __forceinline__ void xcd_barrier(const XcdBarrier& b) {
;     ...
;             __builtin_amdgcn_fence(__ATOMIC_RELEASE, "agent");
;             asm volatile("s_waitcnt vmcnt(0)" ::: "memory");
;             const unsigned og = xb_add(&bar[XB_TOP], 1u);
;             const unsigned tg = og / nx;
;             if (og + 1u == (tg + 1u) * nx) xb_add(&bar[XB_TOPGEN], 1u);
;             else XB_SPIN(xb_ld(&bar[XB_TOPGEN]) == tg, bar);
;             __builtin_amdgcn_fence(__ATOMIC_ACQUIRE, "agent");
;             xb_add(&bar[XB_XGEN(bx)], 1u);
;             asm volatile("s_waitcnt vmcnt(0)" ::: "memory");
.LBB0_819:
	s_or_b64 exec, exec, s[4:5]
	s_mov_b64 s[4:5], exec
	v_mbcnt_lo_u32_b32 v2, s4, 0
	v_mbcnt_hi_u32_b32 v2, s5, v2
	v_cmp_eq_u32_e32 vcc, 0, v2
	s_waitcnt vmcnt(0)
	s_and_saveexec_b64 s[6:7], vcc
	s_cbranch_execz .LBB0_821
	s_add_i32 s82, s20, 0x900
	s_lshl_b64 s[8:9], s[82:83], 2
	s_add_u32 s8, s78, s8
	s_addc_u32 s9, s79, s9
	s_bcnt1_i32_b64 s4, s[4:5]
	v_mov_b32_e32 v2, s4
	global_atomic_add v169, v2, s[8:9]
.LBB0_821:
	s_or_b64 exec, exec, s[6:7]
	buffer_inv sc1
	s_waitcnt vmcnt(0)

; #define LAS __attribute__((address_space(3)))
; __device__ __forceinline__ void phase_attn(Frame& F, const Params& p, int j) {
;     ...
;         const int blk = u & 63, bk = u >> 6, b = bk >> 2, kvh = bk & 3, h = kvh * 8 + F.wave;
;         const float sink = p.in[14][j * 32 + h];
;         const int q_lo = blk == 0 ? 0 : 80 + 64 * (blk - 1), nmt = blk == 0 ? 5 : 4;
;         const int k_lo = q_lo - 128 > 0 ? q_lo - 128 : 0, nk = q_lo + 16 * nmt - k_lo;
;         const bf16_t* Kb = F.KN + ((size_t)bk * LP + k_lo) * 64;
;         const bf16_t* Vb = F.VT + (size_t)bk * 64 * VT_PITCH + k_lo;
;         bf16x8 qfa[5][2];
; #pragma unroll
;         for (int mt = 0; mt < 5; ++mt) { const int mm = mt < nmt ? mt : 0; const bf16_t* qp = QN + (size_t)prow(b, q_lo + 16 * mm + fr) * D + h * 64 + fq * 8;
;             qfa[mt][0] = *(const bf16x8*)qp; qfa[mt][1] = *(const bf16x8*)(qp + 32); }
;         __syncthreads();
;         for (int c = F.tid; c < nk * 8; c += 512) { const int key = c >> 3, part = c & 7;
;             *(LAS u32x4*)(F.lds + key * KSTR + part * 16) = *((const u32x4*)Kb + c); }
;         { const int cpr = nk >> 3;
;           for (int c = F.tid; c < 64 * cpr; c += 512) { const int row = c / cpr, part = c - row * cpr;
;             *(LAS u32x4*)(F.lds + VOFF + row * VSTR + part * 16) = *((const u32x4*)(Vb + (size_t)row * VT_PITCH) + part); } }
.LBB0_1297:
	s_ashr_i32 s20, s24, 6
	s_lshl_b32 s10, s20, 3
	s_and_b32 s18, s10, 24
	s_add_i32 s18, s18, s50
	s_add_i32 s82, s18, s48
	v_readlane_b32 s52, v254, 4
	s_and_b32 s14, s24, 63
	s_ashr_i32 s16, s24, 8
	s_lshl_b64 s[10:11], s[82:83], 2
	v_readlane_b32 s64, v254, 16
	v_readlane_b32 s65, v254, 17
	s_add_u32 s10, s64, s10
	s_addc_u32 s11, s65, s11
	s_cmp_eq_u32 s14, 0
	global_load_dword v73, v169, s[10:11]
	s_cselect_b64 s[12:13], -1, 0
	s_lshl_b32 s10, s14, 6
	s_or_b32 s17, s10, 16
	s_cmp_lg_u32 s14, 0
	s_cselect_b64 s[10:11], -1, 0
	s_and_b64 s[14:15], s[10:11], exec
	s_cselect_b32 s14, 64, 0x50
	s_cselect_b32 s30, s17, 0
	s_cselect_b32 s15, s17, 64
	s_lshl_b32 s25, s16, 12
	s_waitcnt vmcnt(18)
	v_add_u32_e32 v6, s25, v66
	v_lshl_add_u32 v74, s16, 4, v49
	s_waitcnt vmcnt(17)
	v_add_u32_e32 v4, s17, v6
	v_cndmask_b32_e64 v4, v74, v4, s[10:11]
	s_lshl_b32 s82, s18, 7
	v_ashrrev_i32_e32 v5, 31, v4
	v_lshl_add_u64 v[2:3], v[44:45], 0, s[82:83]
	v_lshlrev_b64 v[4:5], 12, v[4:5]
	v_lshl_add_u64 v[4:5], v[2:3], 0, v[4:5]
	s_add_i32 s31, s30, 16
	global_load_dwordx4 v[38:41], v[4:5], off
	global_load_dwordx4 v[34:37], v[4:5], off offset:64
	v_add_u32_e32 v4, s31, v6
	v_ashrrev_i32_e32 v5, 31, v4
	v_lshlrev_b64 v[4:5], 12, v[4:5]
	v_lshl_add_u64 v[4:5], v[2:3], 0, v[4:5]
	s_or_b32 s29, s30, 32
	global_load_dwordx4 v[30:33], v[4:5], off
	global_load_dwordx4 v[26:29], v[4:5], off offset:64
	v_add_u32_e32 v4, s29, v6
	v_ashrrev_i32_e32 v5, 31, v4
	v_lshlrev_b64 v[4:5], 12, v[4:5]
	v_lshl_add_u64 v[4:5], v[2:3], 0, v[4:5]
	s_add_i32 s28, s30, 48
	global_load_dwordx4 v[22:25], v[4:5], off
	global_load_dwordx4 v[18:21], v[4:5], off offset:64
	v_add_u32_e32 v4, s28, v6
	v_ashrrev_i32_e32 v5, 31, v4
	v_lshlrev_b64 v[4:5], 12, v[4:5]
	v_lshl_add_u64 v[4:5], v[2:3], 0, v[4:5]
	global_load_dwordx4 v[14:17], v[4:5], off
	global_load_dwordx4 v[10:13], v[4:5], off offset:64
	v_add_u32_e32 v4, s15, v6
	v_ashrrev_i32_e32 v5, 31, v4
	v_lshlrev_b64 v[4:5], 12, v[4:5]
	v_lshl_add_u64 v[2:3], v[2:3], 0, v[4:5]
	global_load_dwordx4 v[6:9], v[2:3], off
	s_nop 0
	global_load_dwordx4 v[2:5], v[2:3], off offset:64
	v_mov_b32_e32 v54, 0x80
	v_sub_u32_e64 v54, s30, v54 clamp
	s_add_i32 s14, s30, s14
	v_readfirstlane_b32 s27, v54
	s_sub_i32 s34, s14, s27
	s_lshl_b32 s19, s34, 3
	v_cmp_gt_i32_e32 vcc, s19, v42
	v_readlane_b32 s53, v254, 5
	v_readlane_b32 s54, v254, 6
	v_readlane_b32 s55, v254, 7
	v_readlane_b32 s56, v254, 8
	v_readlane_b32 s57, v254, 9
	v_readlane_b32 s58, v254, 10
	v_readlane_b32 s59, v254, 11
	v_readlane_b32 s60, v254, 12
	v_readlane_b32 s61, v254, 13
	v_readlane_b32 s62, v254, 14
	v_readlane_b32 s63, v254, 15
	v_readlane_b32 s66, v254, 18
	v_readlane_b32 s67, v254, 19
	s_barrier
	s_and_saveexec_b64 s[14:15], vcc
	s_cbranch_execz .LBB0_1302
	s_mul_i32 s16, s20, 0x1010
	s_mul_hi_i32 s17, s20, 0x1010
	s_add_u32 s16, s16, s27
	s_addc_u32 s17, s17, 0
	s_lshl_b64 s[16:17], s[16:17], 7
	v_lshl_add_u64 v[54:55], v[50:51], 0, s[16:17]
	s_mul_hi_i32 s17, s20, 0x84000
	s_mul_i32 s16, s20, 0x84000
	s_lshl_b32 s35, s27, 1
	s_or_b32 s16, s16, s35
	s_ashr_i32 s20, s34, 3
	s_abs_i32 s26, s20
	s_lshl_b32 s34, s34, 1
	v_lshl_add_u64 v[56:57], v[52:53], 0, s[16:17]
	s_mov_b64 s[16:17], exec
	v_and_b32_e32 v63, 0x70, v71
	v_lshrrev_b32_e32 v59, 3, v42
	global_load_dwordx4 v[76:79], v[54:55], off
	v_mul_lo_u32 v59, v59, s80
	v_add_u32_e32 v100, v59, v63
	v_add_u32_e32 v59, 0x200, v42
	v_cmp_gt_i32_e32 vcc, s19, v59
	v_lshrrev_b32_e32 v59, 3, v59
	v_lshl_add_u64 v[54:55], v[54:55], 0, s[92:93]
	s_mov_b64 exec, vcc
	global_load_dwordx4 v[80:83], v[54:55], off
	s_mov_b64 exec, s[16:17]
	v_mul_lo_u32 v59, v59, s80
	v_add_u32_e32 v101, v59, v63
	v_add_u32_e32 v59, 0x400, v42
	v_cmp_gt_i32_e32 vcc, s19, v59
	v_lshrrev_b32_e32 v59, 3, v59
	v_lshl_add_u64 v[54:55], v[54:55], 0, s[92:93]
	s_mov_b64 exec, vcc
	global_load_dwordx4 v[84:87], v[54:55], off
	s_mov_b64 exec, s[16:17]
	v_mul_lo_u32 v59, v59, s80
	v_add_u32_e32 v102, v59, v63
	v_cvt_f32_u32_e32 v58, s26
	s_sub_i32 s35, 0, s26
	v_rcp_iflag_f32_e32 v58, v58
	s_nop 0
	v_mul_f32_e32 v58, 0x4f7ffffe, v58
	v_cvt_u32_f32_e32 v58, v58
	v_mul_lo_u32 v59, s35, v58
	v_mul_hi_u32 v59, v58, v59
	v_add_u32_e32 v58, v58, v59
	s_movk_i32 s35, 0x190
	v_mul_hi_u32 v60, v42, v58
	v_mul_lo_u32 v61, v60, s26
	v_sub_u32_e32 v61, v42, v61
	v_cmp_le_u32_e32 vcc, s26, v61
	v_add_u32_e32 v62, 1, v60
	v_subrev_u32_e32 v63, s26, v61
	v_cndmask_b32_e32 v60, v60, v62, vcc
	v_cndmask_b32_e32 v61, v61, v63, vcc
	v_cmp_le_u32_e32 vcc, s26, v61
	v_add_u32_e32 v62, 1, v60
	s_nop 1
	v_cndmask_b32_e32 v60, v60, v62, vcc
	v_mul_lo_u32 v61, v60, s34
	v_mul_lo_u32 v62, v60, s90
	v_mul_lo_u32 v63, v60, s35
	v_sub_u32_e32 v62, v62, v61
	v_sub_u32_e32 v63, v63, v61
	v_add_u32_e32 v103, v43, v63
	v_add_co_u32_e32 v60, vcc, v56, v62
	s_nop 1
	v_addc_co_u32_e32 v61, vcc, 0, v57, vcc
	global_load_dwordx4 v[88:91], v[60:61], off
	v_lshl_add_u64 v[56:57], v[56:57], 0, s[92:93]
	v_add_u32_e32 v59, 0x200, v42
	v_mul_hi_u32 v60, v59, v58
	v_mul_lo_u32 v61, v60, s26
	v_sub_u32_e32 v61, v59, v61
	v_cmp_le_u32_e32 vcc, s26, v61
	v_add_u32_e32 v62, 1, v60
	v_subrev_u32_e32 v63, s26, v61
	v_cndmask_b32_e32 v60, v60, v62, vcc
	v_cndmask_b32_e32 v61, v61, v63, vcc
	v_cmp_le_u32_e32 vcc, s26, v61
	v_add_u32_e32 v62, 1, v60
	s_nop 1
	v_cndmask_b32_e32 v60, v60, v62, vcc
	v_mul_lo_u32 v61, v60, s34
	v_mul_lo_u32 v62, v60, s90
	v_mul_lo_u32 v63, v60, s35
	v_sub_u32_e32 v62, v62, v61
	v_sub_u32_e32 v63, v63, v61
	v_add_u32_e32 v64, v43, v63
	v_add_u32_e32 v64, 0x2000, v64
	v_add_co_u32_e32 v60, vcc, v56, v62
	s_nop 1
	v_addc_co_u32_e32 v61, vcc, 0, v57, vcc
	v_cmp_gt_i32_e32 vcc, s19, v59
	s_nop 0
	s_mov_b64 exec, vcc
	global_load_dwordx4 v[92:95], v[60:61], off
	s_mov_b64 exec, s[16:17]
	v_lshl_add_u64 v[56:57], v[56:57], 0, s[92:93]
	v_add_u32_e32 v59, 0x400, v42
	v_mul_hi_u32 v60, v59, v58
	v_mul_lo_u32 v61, v60, s26
	v_sub_u32_e32 v61, v59, v61
	v_cmp_le_u32_e32 vcc, s26, v61
	v_add_u32_e32 v62, 1, v60
	v_subrev_u32_e32 v63, s26, v61
	v_cndmask_b32_e32 v60, v60, v62, vcc
	v_cndmask_b32_e32 v61, v61, v63, vcc
	v_cmp_le_u32_e32 vcc, s26, v61
	v_add_u32_e32 v62, 1, v60
	s_nop 1
	v_cndmask_b32_e32 v60, v60, v62, vcc
	v_mul_lo_u32 v61, v60, s34
	v_mul_lo_u32 v62, v60, s90
	v_mul_lo_u32 v63, v60, s35
	v_sub_u32_e32 v62, v62, v61
	v_sub_u32_e32 v63, v63, v61
	v_add_u32_e32 v65, v43, v63
	v_add_u32_e32 v65, 0x4000, v65
	v_add_co_u32_e32 v60, vcc, v56, v62
	s_nop 1
	v_addc_co_u32_e32 v61, vcc, 0, v57, vcc
	v_cmp_gt_i32_e32 vcc, s19, v59
	s_nop 0
	s_mov_b64 exec, vcc
	global_load_dwordx4 v[96:99], v[60:61], off
	s_mov_b64 exec, s[16:17]
	s_waitcnt vmcnt(3)
	ds_write_b128 v100, v[76:79]
	v_add_u32_e32 v59, 0x200, v42
	v_add_u32_e32 v60, 0x400, v42
	v_cmp_gt_i32_e32 vcc, s19, v59
	v_cmp_gt_i32_e64 s[36:37], s19, v60
	s_waitcnt vmcnt(0)
	ds_write_b128 v103, v[88:91]
	s_mov_b64 exec, vcc
	ds_write_b128 v101, v[80:83]
	ds_write_b128 v64, v[92:95]
	s_mov_b64 exec, s[36:37]
	ds_write_b128 v102, v[84:87]
	ds_write_b128 v65, v[96:99]

; __device__ __forceinline__ unsigned xb_ld(unsigned* p)              { return __hip_atomic_load(p, __ATOMIC_RELAXED, __HIP_MEMORY_SCOPE_AGENT); }
; __device__ __forceinline__ unsigned xb_add(unsigned* p, unsigned v) { return __hip_atomic_fetch_add(p, v, __ATOMIC_RELAXED, __HIP_MEMORY_SCOPE_AGENT); }
; #define XB_SPIN(cond, bar) do { unsigned _sp = 0; while (cond) { __builtin_amdgcn_s_sleep(1); \
;     if ((++_sp & 255u) == 0u) { if (xb_ld(&(bar)[XB_TMO])) break; if (_sp > XB_SPIN_CAP) { atomicAdd(&(bar)[XB_TMO], 1u); break; } } } } while (0)
; __device__ __forceinline__ void xcd_barrier(const XcdBarrier& b) {
;     ...
;             __builtin_amdgcn_fence(__ATOMIC_RELEASE, "agent");
;             asm volatile("s_waitcnt vmcnt(0)" ::: "memory");
;             const unsigned og = xb_add(&bar[XB_TOP], 1u);
;             const unsigned tg = og / nx;
;             if (og + 1u == (tg + 1u) * nx) xb_add(&bar[XB_TOPGEN], 1u);
;             else XB_SPIN(xb_ld(&bar[XB_TOPGEN]) == tg, bar);
;             __builtin_amdgcn_fence(__ATOMIC_ACQUIRE, "agent");
;             xb_add(&bar[XB_XGEN(bx)], 1u);
;             asm volatile("s_waitcnt vmcnt(0)" ::: "memory");
.LBB0_2362:
	s_or_b64 exec, exec, s[4:5]
	s_mov_b64 s[4:5], exec
	v_mbcnt_lo_u32_b32 v2, s4, 0
	v_mbcnt_hi_u32_b32 v2, s5, v2
	v_cmp_eq_u32_e32 vcc, 0, v2
	s_waitcnt vmcnt(0)
	s_and_saveexec_b64 s[6:7], vcc
	s_cbranch_execz .LBB0_2364
	s_add_i32 s82, s22, 0x900
	s_lshl_b64 s[8:9], s[82:83], 2
	s_add_u32 s8, s78, s8
	s_addc_u32 s9, s79, s9
	s_bcnt1_i32_b64 s4, s[4:5]
	v_mov_b32_e32 v2, s4
	global_atomic_add v169, v2, s[8:9]

; __device__ __forceinline__ unsigned xb_ld(unsigned* p)              { return __hip_atomic_load(p, __ATOMIC_RELAXED, __HIP_MEMORY_SCOPE_AGENT); }
; __device__ __forceinline__ unsigned xb_add(unsigned* p, unsigned v) { return __hip_atomic_fetch_add(p, v, __ATOMIC_RELAXED, __HIP_MEMORY_SCOPE_AGENT); }
; #define XB_SPIN(cond, bar) do { unsigned _sp = 0; while (cond) { __builtin_amdgcn_s_sleep(1); \
;     if ((++_sp & 255u) == 0u) { if (xb_ld(&(bar)[XB_TMO])) break; if (_sp > XB_SPIN_CAP) { atomicAdd(&(bar)[XB_TMO], 1u); break; } } } } while (0)
; __device__ __forceinline__ void xcd_barrier(const XcdBarrier& b) {
;     ...
;             __builtin_amdgcn_fence(__ATOMIC_RELEASE, "agent");
;             asm volatile("s_waitcnt vmcnt(0)" ::: "memory");
;             const unsigned og = xb_add(&bar[XB_TOP], 1u);
;             const unsigned tg = og / nx;
;             if (og + 1u == (tg + 1u) * nx) xb_add(&bar[XB_TOPGEN], 1u);
;             else XB_SPIN(xb_ld(&bar[XB_TOPGEN]) == tg, bar);
;             __builtin_amdgcn_fence(__ATOMIC_ACQUIRE, "agent");
;             xb_add(&bar[XB_XGEN(bx)], 1u);
;             asm volatile("s_waitcnt vmcnt(0)" ::: "memory");
.LBB0_2501:
	s_or_b64 exec, exec, s[4:5]
	s_mov_b64 s[4:5], exec
	v_mbcnt_lo_u32_b32 v2, s4, 0
	v_mbcnt_hi_u32_b32 v2, s5, v2
	v_cmp_eq_u32_e32 vcc, 0, v2
	s_waitcnt vmcnt(0)
	s_and_saveexec_b64 s[6:7], vcc
	s_cbranch_execnz .LBB0_2502
	buffer_inv sc1
	s_getpc_b64 s[98:99]

; __device__ __forceinline__ unsigned xb_ld(unsigned* p)              { return __hip_atomic_load(p, __ATOMIC_RELAXED, __HIP_MEMORY_SCOPE_AGENT); }
; __device__ __forceinline__ unsigned xb_add(unsigned* p, unsigned v) { return __hip_atomic_fetch_add(p, v, __ATOMIC_RELAXED, __HIP_MEMORY_SCOPE_AGENT); }
; #define XB_SPIN(cond, bar) do { unsigned _sp = 0; while (cond) { __builtin_amdgcn_s_sleep(1); \
;     if ((++_sp & 255u) == 0u) { if (xb_ld(&(bar)[XB_TMO])) break; if (_sp > XB_SPIN_CAP) { atomicAdd(&(bar)[XB_TMO], 1u); break; } } } } while (0)
; __device__ __forceinline__ void xcd_barrier(const XcdBarrier& b) {
;     ...
;             __builtin_amdgcn_fence(__ATOMIC_RELEASE, "agent");
;             asm volatile("s_waitcnt vmcnt(0)" ::: "memory");
;             const unsigned og = xb_add(&bar[XB_TOP], 1u);
;             const unsigned tg = og / nx;
;             if (og + 1u == (tg + 1u) * nx) xb_add(&bar[XB_TOPGEN], 1u);
;             else XB_SPIN(xb_ld(&bar[XB_TOPGEN]) == tg, bar);
;             __builtin_amdgcn_fence(__ATOMIC_ACQUIRE, "agent");
;             xb_add(&bar[XB_XGEN(bx)], 1u);
;             asm volatile("s_waitcnt vmcnt(0)" ::: "memory");
.LBB0_2502:
	s_add_i32 s82, s20, 0x900
	s_lshl_b64 s[8:9], s[82:83], 2
	s_add_u32 s8, s78, s8
	s_addc_u32 s9, s79, s9
	s_bcnt1_i32_b64 s4, s[4:5]
	v_mov_b32_e32 v2, s4
	global_atomic_add v169, v2, s[8:9]
	buffer_inv sc1
	s_getpc_b64 s[98:99]
